# loop-edge edit: attention loop's uniform fetch-another-tile test as scalar compare + scc branch (no exec save/restore)
# speedup vs baseline: 1.0114x; 1.0088x over previous
.LBB0_842:
	s_or_b64 exec, exec, s[0:1]
	v_mov_b32_e32 v0, v113
	v_mov_b32_e32 v1, v113
	v_mov_b32_e32 v2, v113
	v_mov_b32_e32 v3, v113
	v_mov_b32_e32 v4, v113
	v_mov_b32_e32 v5, v113
	v_mov_b32_e32 v6, v113
	v_mov_b32_e32 v7, v113
	v_mov_b32_e32 v8, v113
	v_mov_b32_e32 v10, v113
	v_mov_b32_e32 v11, v113
	v_mov_b32_e32 v12, v113
	v_mov_b32_e32 v13, v113
	v_mov_b64_e32 v[30:31], v[14:15]
	v_mov_b64_e32 v[46:47], v[14:15]
	v_mov_b64_e32 v[62:63], v[14:15]
	s_xor_b64 s[46:47], s[8:9], -1
	v_cmp_lt_u32_e64 s[8:9], v145, v127
	v_cmp_ge_u32_e64 s[10:11], v145, v127
	s_mov_b32 s33, 1
	v_mov_b32_e32 v147, v113
	v_lshlrev_b32_e32 v129, 6, v137
	v_mov_b64_e32 v[28:29], v[12:13]
	v_mov_b64_e32 v[26:27], v[10:11]
	v_mov_b64_e32 v[24:25], v[8:9]
	v_mov_b64_e32 v[22:23], v[6:7]
	v_mov_b64_e32 v[20:21], v[4:5]
	v_mov_b64_e32 v[18:19], v[2:3]
	v_mov_b64_e32 v[16:17], v[0:1]
	v_mov_b64_e32 v[44:45], v[12:13]
	v_mov_b64_e32 v[42:43], v[10:11]
	v_mov_b64_e32 v[40:41], v[8:9]
	v_mov_b64_e32 v[38:39], v[6:7]
	v_mov_b64_e32 v[36:37], v[4:5]
	v_mov_b64_e32 v[34:35], v[2:3]
	v_mov_b64_e32 v[32:33], v[0:1]
	v_mov_b64_e32 v[60:61], v[12:13]
	v_mov_b64_e32 v[58:59], v[10:11]
	v_mov_b64_e32 v[56:57], v[8:9]
	v_mov_b64_e32 v[54:55], v[6:7]
	v_mov_b64_e32 v[52:53], v[4:5]
	v_mov_b64_e32 v[50:51], v[2:3]
	v_mov_b64_e32 v[48:49], v[0:1]
	v_mov_b32_e32 v131, 0
	s_waitcnt vmcnt(0)
	v_readfirstlane_b32 s61, v137
	v_subrev_u32_e32 v200, s98, v140
	v_subrev_u32_e32 v204, s100, v142
	v_add_u32_e32 v201, s34, v200
	v_add_u32_e32 v202, s36, v200
	v_add_u32_e32 v203, s38, v200
	v_add_u32_e32 v205, v204, v112
	v_add_u32_e32 v206, v204, v146
	v_add_u32_e32 v207, v204, v148
	v_readfirstlane_b32 s60, v155
	v_xor_b32_e32 v232, 0x80000000, v125
	v_mov_b32_e32 v233, v232
	v_mov_b32_e32 v234, v232
	v_mov_b32_e32 v235, v232
	v_mov_b32_e32 v236, v232
	v_mov_b32_e32 v237, v232
	v_mov_b32_e32 v238, v232
	v_mov_b32_e32 v239, v232
	v_mov_b32_e32 v240, v232
	v_mov_b32_e32 v241, v232
	v_mov_b32_e32 v242, v232
	v_mov_b32_e32 v243, v232
	v_mov_b32_e32 v244, v232
	v_mov_b32_e32 v245, v232
	v_mov_b32_e32 v246, v232
	v_mov_b32_e32 v247, v232
	s_branch .LBB0_845

.LBB0_845:
	s_waitcnt vmcnt(0)
	s_waitcnt lgkmcnt(0)
	s_add_i32 s0, s33, -1
	s_and_b32 s50, s0, 1
	s_barrier
	s_lshl_b32 s58, s50, 15
	v_add_u32_e32 v173, s58, v152
	v_add_u32_e32 v80, v173, v156
	v_add_u32_e32 v182, v173, v157
	v_add_u32_e32 v186, v173, v158
	ds_read_b128 v[174:177], v80
	ds_read_b128 v[178:181], v80 offset:8192
	ds_read_b128 v[208:211], v182
	ds_read_b128 v[182:185], v182 offset:8192
	ds_read_b128 v[212:215], v186
	ds_read_b128 v[186:189], v186 offset:8192
	s_cmp_lt_u32 s33, s61
	s_cbranch_scc0 .LBB0_847
	s_lshl_b32 s48, s50, 15
	s_xor_b32 s48, s48, 0x8000
	s_add_u32 s48, s48, s60
	s_mov_b32 m0, s48
	s_nop 0
	global_load_lds_dwordx4 v200, s[98:99]
	s_add_u32 m0, s48, 0x4000
	s_nop 0
	global_load_lds_dwordx4 v204, s[100:101]
	s_add_u32 m0, s48, 0x1000
	s_nop 0
	global_load_lds_dwordx4 v201, s[98:99]
	s_add_u32 m0, s48, 0x5000
	s_nop 0
	global_load_lds_dwordx4 v205, s[100:101]
	s_add_u32 m0, s48, 0x2000
	s_nop 0
	global_load_lds_dwordx4 v202, s[98:99]
	s_add_u32 m0, s48, 0x6000
	s_nop 0
	global_load_lds_dwordx4 v206, s[100:101]
	s_add_u32 m0, s48, 0x3000
	s_nop 0
	global_load_lds_dwordx4 v203, s[98:99]
	s_add_u32 m0, s48, 0x7000
	s_add_u32 s98, s98, s28
	global_load_lds_dwordx4 v207, s[100:101]
	s_addc_u32 s99, s99, s29
	s_add_u32 s100, s100, s40
	s_addc_u32 s101, s101, s41
.LBB0_847:
	v_add_u32_e32 v133, 64, v172
	s_and_saveexec_b64 s[0:1], s[10:11]
	s_xor_b64 s[0:1], exec, s[0:1]
	v_add_u32_e32 v133, 64, v172
	s_andn2_saveexec_b64 s[48:49], s[0:1]
	s_cbranch_execz .LBB0_844
	s_lshl_b32 s0, s50, 15
	s_add_i32 s58, s0, 0
	v_add_u32_e32 v173, v173, v159
	v_cmp_gt_u32_e32 vcc, v133, v171
	s_waitcnt lgkmcnt(4)
	v_mfma_f32_32x32x16_bf16 v[80:95], v[174:177], v[96:99], v[232:247]
	v_mfma_f32_32x32x16_bf16 v[64:79], v[178:181], v[96:99], v[232:247]
	ds_read_b128 v[174:177], v173
	ds_read_b128 v[190:193], v173 offset:8192
	s_waitcnt lgkmcnt(4)
	v_mfma_f32_32x32x16_bf16 v[80:95], v[208:211], v[100:103], v[80:95]
	v_mfma_f32_32x32x16_bf16 v[64:79], v[182:185], v[100:103], v[64:79]
	s_waitcnt lgkmcnt(2)
	v_mfma_f32_32x32x16_bf16 v[80:95], v[212:215], v[104:107], v[80:95]
	v_mfma_f32_32x32x16_bf16 v[64:79], v[186:189], v[104:107], v[64:79]
	s_waitcnt lgkmcnt(0)
	v_mfma_f32_32x32x16_bf16 v[80:95], v[174:177], v[108:111], v[80:95]
	v_mfma_f32_32x32x16_bf16 v[64:79], v[190:193], v[108:111], v[64:79]
	s_and_saveexec_b64 s[50:51], vcc
	s_cbranch_execz .LBB0_852
	v_add_u32_e32 v172, v114, v172
	v_add_u32_e32 v173, 1, v172
	v_cmp_lt_u32_e32 vcc, v172, v171
	v_cmp_lt_u32_e64 s[0:1], v173, v171
	s_or_b64 vcc, s[0:1], vcc
	v_add_u32_e32 v173, 2, v172
	s_nop 2
	v_cndmask_b32_e32 v80, v169, v80, vcc
	v_cmp_lt_u32_e32 vcc, v173, v171
	v_add_u32_e32 v173, 3, v172
	v_cndmask_b32_e64 v81, v169, v81, s[0:1]
	v_cndmask_b32_e32 v82, v169, v82, vcc
	v_cmp_lt_u32_e32 vcc, v173, v171
	v_add_u32_e32 v173, 4, v172
	s_nop 0
	v_cndmask_b32_e32 v83, v169, v83, vcc
	v_cmp_lt_u32_e32 vcc, v173, v171
	v_add_u32_e32 v173, 5, v172
	s_nop 0
	v_cndmask_b32_e32 v84, v169, v84, vcc
	v_cmp_lt_u32_e32 vcc, v173, v171
	v_add_u32_e32 v173, 6, v172
	s_nop 0
	v_cndmask_b32_e32 v85, v169, v85, vcc
	v_cmp_lt_u32_e32 vcc, v173, v171
	v_add_u32_e32 v173, 7, v172
	s_nop 0
	v_cndmask_b32_e32 v86, v169, v86, vcc
	v_cmp_lt_u32_e32 vcc, v173, v171
	v_add_u32_e32 v173, 16, v172
	s_nop 0
	v_cndmask_b32_e32 v87, v169, v87, vcc
	v_cmp_lt_u32_e32 vcc, v173, v171
	v_add_u32_e32 v173, 17, v172
	s_nop 0
	v_cndmask_b32_e32 v88, v169, v88, vcc
	v_cmp_lt_u32_e32 vcc, v173, v171
	v_add_u32_e32 v173, 18, v172
	s_nop 0
	v_cndmask_b32_e32 v89, v169, v89, vcc
	v_cmp_lt_u32_e32 vcc, v173, v171
	v_add_u32_e32 v173, 19, v172
	s_nop 0
	v_cndmask_b32_e32 v90, v169, v90, vcc
	v_cmp_lt_u32_e32 vcc, v173, v171
	v_add_u32_e32 v173, 20, v172
	s_nop 0
	v_cndmask_b32_e32 v91, v169, v91, vcc
	v_cmp_lt_u32_e32 vcc, v173, v171
	v_add_u32_e32 v173, 21, v172
	s_nop 0
	v_cndmask_b32_e32 v92, v169, v92, vcc
	v_cmp_lt_u32_e32 vcc, v173, v171
	v_add_u32_e32 v173, 22, v172
	s_nop 0
	v_cndmask_b32_e32 v93, v169, v93, vcc
	v_cmp_lt_u32_e32 vcc, v173, v171
	v_add_u32_e32 v173, 23, v172
	s_nop 0
	v_cndmask_b32_e32 v94, v169, v94, vcc
	v_cmp_lt_u32_e32 vcc, v173, v171
	v_add_u32_e32 v173, 32, v172
	v_cmp_lt_u32_e64 s[0:1], v173, v171
	s_or_b64 vcc, s[0:1], vcc
	v_add_u32_e32 v173, 33, v172
	v_cndmask_b32_e32 v95, v169, v95, vcc
	v_cmp_lt_u32_e32 vcc, v173, v171
	v_add_u32_e32 v173, 34, v172
	v_cndmask_b32_e64 v64, v169, v64, s[0:1]
	v_cndmask_b32_e32 v65, v169, v65, vcc
	v_cmp_lt_u32_e32 vcc, v173, v171
	v_add_u32_e32 v173, 35, v172
	s_nop 0
	v_cndmask_b32_e32 v66, v169, v66, vcc
	v_cmp_lt_u32_e32 vcc, v173, v171
	v_add_u32_e32 v173, 36, v172
	s_nop 0
	v_cndmask_b32_e32 v67, v169, v67, vcc
	v_cmp_lt_u32_e32 vcc, v173, v171
	v_add_u32_e32 v173, 37, v172
	s_nop 0
	v_cndmask_b32_e32 v68, v169, v68, vcc
	v_cmp_lt_u32_e32 vcc, v173, v171
	v_add_u32_e32 v173, 38, v172
	s_nop 0
	v_cndmask_b32_e32 v69, v169, v69, vcc
	v_cmp_lt_u32_e32 vcc, v173, v171
	v_add_u32_e32 v173, 39, v172
	s_nop 0
	v_cndmask_b32_e32 v70, v169, v70, vcc
	v_cmp_lt_u32_e32 vcc, v173, v171
	v_add_u32_e32 v173, 48, v172
	s_nop 0
	v_cndmask_b32_e32 v71, v169, v71, vcc
	v_cmp_lt_u32_e32 vcc, v173, v171
	v_add_u32_e32 v173, 49, v172
	s_nop 0
	v_cndmask_b32_e32 v72, v169, v72, vcc
	v_cmp_lt_u32_e32 vcc, v173, v171
	v_add_u32_e32 v173, 50, v172
	s_nop 0
	v_cndmask_b32_e32 v73, v169, v73, vcc
	v_cmp_lt_u32_e32 vcc, v173, v171
	v_add_u32_e32 v173, 51, v172
	s_nop 0
	v_cndmask_b32_e32 v74, v169, v74, vcc
	v_cmp_lt_u32_e32 vcc, v173, v171
	v_add_u32_e32 v173, 52, v172
	s_nop 0
	v_cndmask_b32_e32 v75, v169, v75, vcc
	v_cmp_lt_u32_e32 vcc, v173, v171
	v_add_u32_e32 v173, 53, v172
	s_nop 0
	v_cndmask_b32_e32 v76, v169, v76, vcc
	v_cmp_lt_u32_e32 vcc, v173, v171
	v_add_u32_e32 v173, 54, v172
	v_add_u32_e32 v172, 55, v172
	v_cndmask_b32_e32 v77, v169, v77, vcc
	v_cmp_lt_u32_e32 vcc, v173, v171
	s_nop 1
	v_cndmask_b32_e32 v78, v169, v78, vcc
	v_cmp_lt_u32_e32 vcc, v172, v171
	s_nop 1
	v_cndmask_b32_e32 v79, v169, v79, vcc
